# inproj phase: XCD-aware static item mapping (rank within the XCD from one atomic, stride = workgroups on the XCD): each XCD takes 12 of the 24 N-tiles and a quarter of the M-tiles, so an xn row tile i
# baseline (speedup 1.0000x reference)
; DI void phase_inproj(const Params& p, int l, char* smem, int tid) {
;     ...
;   for (int it = blockIdx.x; it < 272 * 24; it += gridDim.x) {
;     const int mt = it / 24, nt = it % 24, m0 = mt * 128, n0 = nt * 128;
;     f32x16 acc[2][2]; zero_acc<2>(acc);
;     gemm_main<2>(p.xn + (size_t)m0 * 1024, 1024, Wt + (size_t)n0 * 1024, 1024, 1024, acc, s, tid);
.LBB0_515:
	v_readlane_b32 s0, v253, 14
	v_readlane_b32 s1, v253, 15
	v_mov_b32_e32 v0, v206
	s_andn2_b64 vcc, exec, s[0:1]
	s_cbranch_vccnz .LBB0_550
	v_readlane_b32 s0, v254, 19
	v_and_b32_e32 v113, 63, v206
	v_lshrrev_b32_e32 v114, 6, v206
	v_lshrrev_b32_e32 v115, 3, v113
	v_lshl_add_u32 v115, v114, 5, v115
	v_lshlrev_b32_e32 v115, 11, v115
	v_and_b32_e32 v116, 7, v113
	v_lshrrev_b32_e32 v113, 4, v113
	v_xor_b32_e32 v116, v116, v113
	v_lshl_or_b32 v98, v116, 4, v115
	v_xor_b32_e32 v99, 64, v98
	v_add_u32_e32 v99, 16384, v99
	v_add_u32_e32 v100, 32768, v98
	v_add_u32_e32 v101, 32768, v99
	v_lshrrev_b32_e32 v117, 6, v206
	v_and_b32_e32 v113, 31, v206
	v_bfe_u32 v114, v206, 5, 1
	v_bfe_u32 v115, v113, 1, 3
	v_xor_b32_e32 v115, v115, v114
	v_lshlrev_b32_e32 v115, 4, v115
	v_lshl_or_b32 v115, v113, 7, v115
	v_lshrrev_b32_e32 v116, 7, v206
	v_lshl_add_u32 v102, v116, 13, v115
	v_bfe_u32 v116, v206, 6, 1
	v_lshl_add_u32 v106, v116, 13, v115
	v_add_u32_e32 v106, 0x4000, v106
	v_xor_b32_e32 v103, 32, v102
	v_xor_b32_e32 v107, 32, v106
	v_xor_b32_e32 v104, 64, v102
	v_xor_b32_e32 v108, 64, v106
	v_xor_b32_e32 v105, 96, v102
	v_xor_b32_e32 v109, 96, v106
	v_and_b32_e32 v113, 31, v206
	v_lshrrev_b32_e32 v114, 7, v206
	v_lshl_add_u32 v113, v114, 6, v113
	v_bfe_u32 v115, v206, 5, 1
	v_lshlrev_b32_e32 v116, 3, v115
	v_mul_u32_u24_e32 v110, 0xe00, v113
	v_add_u32_e32 v110, v110, v116
	v_mul_u32_u24_e32 v111, 0x640, v113
	v_add_u32_e32 v111, v111, v116
	v_mul_u32_u24_e32 v116, 0x8800, v115
	v_lshl_add_u32 v112, v113, 1, v116
	v_lshrrev_b32_e32 v113, 6, v206
	v_mul_u32_u24_e32 v113, 0x2400, v113
	v_add_u32_e32 v113, 0x8000, v113
	v_and_b32_e32 v114, 31, v206
	v_mul_u32_u24_e32 v114, 0x90, v114
	v_bfe_u32 v115, v206, 5, 1
	v_lshl_add_u32 v114, v115, 3, v114
	v_add_u32_e32 v118, v113, v114
	v_bfe_u32 v114, v206, 3, 3
	v_mul_u32_u24_e32 v114, 0x90, v114
	v_and_b32_e32 v115, 7, v206
	v_lshl_add_u32 v114, v115, 4, v114
	v_add_u32_e32 v119, v113, v114
	v_bfe_u32 v113, v206, 3, 3
	v_lshrrev_b32_e32 v114, 7, v206
	v_lshl_add_u32 v113, v114, 6, v113
	v_mul_u32_u24_e32 v113, 0xe00, v113
	v_bfe_u32 v114, v206, 6, 1
	v_lshlrev_b32_e32 v114, 7, v114
	v_and_b32_e32 v115, 7, v206
	v_lshl_or_b32 v114, v115, 4, v114
	v_add_u32_e32 v120, v113, v114
	v_bfe_u32 v113, v206, 3, 3
	v_lshrrev_b32_e32 v114, 7, v206
	v_lshl_add_u32 v113, v114, 6, v113
	v_mul_u32_u24_e32 v113, 0x640, v113
	v_bfe_u32 v114, v206, 6, 1
	v_lshlrev_b32_e32 v114, 7, v114
	v_and_b32_e32 v115, 7, v206
	v_lshl_or_b32 v114, v115, 4, v114
	v_add_u32_e32 v121, v113, v114
	v_readfirstlane_b32 s10, v117
	s_lshl_b32 s10, s10, 12
	s_mul_i32 s1, s0, 0x600000
	s_add_u32 s14, s96, 0x1ab20000
	s_addc_u32 s15, s97, 0
	s_add_u32 s14, s14, s1
	s_addc_u32 s15, s15, 0
	v_readlane_b32 s0, v254, 19
	s_getreg_b32 s16, hwreg(HW_REG_XCC_ID, 0, 4)
	s_cmp_eq_u32 s10, 0
	s_cbranch_scc0 .Lipx_wait
	s_mov_b64 s[6:7], exec
	s_mov_b64 exec, 1
	s_lshl_b32 s8, s16, 8
	s_lshl_b32 s9, s0, 11
	s_add_u32 s8, s8, s9
	s_add_u32 s8, s8, 0x1da60000
	s_add_u32 s8, s96, s8
	s_addc_u32 s9, s97, 0
	v_mov_b32_e32 v113, 1
	v_mov_b32_e32 v114, 0
	global_atomic_add v115, v114, v113, s[8:9] sc0
	v_mov_b32_e32 v116, 0x125f0
	s_waitcnt vmcnt(0)
	ds_write_b32 v116, v115
	s_waitcnt lgkmcnt(0)
	s_mov_b64 exec, s[6:7]
.Lipx_wait:
	s_barrier
	v_mov_b32_e32 v116, 0x125f0
	ds_read_b32 v115, v116
	ds_read_b32 v114, v116 offset:16
	s_waitcnt lgkmcnt(0)
	v_readfirstlane_b32 s12, v115
	v_readfirstlane_b32 s17, v114
	s_lshr_b32 s2, s16, 1
	s_lshl_b32 s2, s2, 8
	s_or_b32 s17, s17, s2
	s_and_b32 s2, s16, 1
	s_mul_i32 s2, s2, 12
	s_lshl_b32 s2, s2, 16
	s_or_b32 s17, s17, s2
	s_cmpk_lt_u32 s12, 0x330
	s_cbranch_scc0 .Lip_done
	s_mul_hi_u32 s0, s12, 0xaaaaaaab
	s_lshr_b32 s0, s0, 3
	s_mul_i32 s2, s0, 12
	s_sub_u32 s1, s12, s2
	s_bfe_u32 s2, s17, 0x80010
	s_add_u32 s1, s1, s2
	s_lshl_b32 s0, s0, 2
	s_bfe_u32 s2, s17, 0x80008
	s_add_u32 s0, s0, s2
	s_lshl_b32 s2, s0, 18
	s_add_u32 s4, s96, s2
	s_addc_u32 s5, s97, 0
	s_lshl_b32 s2, s1, 18
	s_add_u32 s8, s14, s2
	s_addc_u32 s9, s15, 0
	s_add_u32 m0, s10, 0x0
	s_nop 0
	global_load_lds_dwordx4 v98, s[4:5]
	s_add_u32 m0, s10, 0x400
	s_nop 0
	global_load_lds_dwordx4 v99, s[4:5]
	s_add_u32 m0, s10, 0x800
	s_nop 0
	global_load_lds_dwordx4 v100, s[4:5]
	s_add_u32 m0, s10, 0xc00
	s_nop 0
	global_load_lds_dwordx4 v101, s[4:5]
	s_add_u32 m0, s10, 0x4000
	s_nop 0
	global_load_lds_dwordx4 v98, s[8:9]
	s_add_u32 m0, s10, 0x4400
	s_nop 0
	global_load_lds_dwordx4 v99, s[8:9]
	s_add_u32 m0, s10, 0x4800
	s_nop 0
	global_load_lds_dwordx4 v100, s[8:9]
	s_add_u32 m0, s10, 0x4c00
	s_nop 0
	global_load_lds_dwordx4 v101, s[8:9]
	s_add_u32 s4, s4, 128
	s_addc_u32 s5, s5, 0
	s_add_u32 s8, s8, 128
	s_addc_u32 s9, s9, 0
.Lip_item:
	s_mul_hi_u32 s0, s12, 0xaaaaaaab
	s_lshr_b32 s0, s0, 3
	s_mul_i32 s2, s0, 12
	s_sub_u32 s1, s12, s2
	s_bfe_u32 s2, s17, 0x80010
	s_add_u32 s1, s1, s2
	s_lshl_b32 s0, s0, 2
	s_bfe_u32 s2, s17, 0x80008
	s_add_u32 s0, s0, s2
	s_mov_b32 s94, 0

; #define G_STORE(S, bf) { *(uint4*)&s->a[bf][srow][skc] = S##a0; *(uint4*)&s->a[bf][srow + 32][skc] = S##a1; \
;     if (MB == 2) { *(uint4*)&s->a[bf][srow + 64][skc] = S##a2; *(uint4*)&s->a[bf][srow + 96][skc] = S##a3; } \
;     *(uint4*)&s->b[bf][srow][skc] = S##b0; *(uint4*)&s->b[bf][srow + 32][skc] = S##b1; *(uint4*)&s->b[bf][srow + 64][skc] = S##b2; *(uint4*)&s->b[bf][srow + 96][skc] = S##b3; }
; template <int MB, bool PF2 = true>
; DI void gemm_main(const u16* __restrict__ A, int lda, const u16* __restrict__ B, int ldb, int K, f32x16 (&acc)[MB][2], GemmLds* s, int tid) {
;     ...
;   for (int kt = 0; kt < KT; kt += 2) {
;     { const int k2 = min((kt + 2) * 64, klast); G_LOAD(q, k2); }
;     __builtin_amdgcn_sched_barrier(0);
;     G_COMPUTE(0);
;     G_STORE(p, 1);
;     __syncthreads();
;     { const int k3 = min((kt + 3) * 64, klast); G_LOAD(p, k3); }
;     __builtin_amdgcn_sched_barrier(0);
;     G_COMPUTE(1);
;     G_STORE(q, 0);
;     __syncthreads();
; DI void phase_inproj(const Params& p, int l, char* smem, int tid) {
;     ...
;   for (int it = blockIdx.x; it < 272 * 24; it += gridDim.x) {
;     const int mt = it / 24, nt = it % 24, m0 = mt * 128, n0 = nt * 128;
;     f32x16 acc[2][2]; zero_acc<2>(acc);
;     gemm_main<2>(p.xn + (size_t)m0 * 1024, 1024, Wt + (size_t)n0 * 1024, 1024, 1024, acc, s, tid);
.Lip_last:
	s_and_b32 s6, s17, 0xff
	s_add_u32 s6, s12, s6
	s_cmpk_lt_u32 s6, 0x330
	s_cbranch_scc0 .Lip_nopf
	s_mul_hi_u32 s2, s6, 0xaaaaaaab
	s_lshr_b32 s2, s2, 3
	s_mul_i32 s4, s2, 12
	s_sub_u32 s3, s6, s4
	s_bfe_u32 s4, s17, 0x80010
	s_add_u32 s3, s3, s4
	s_lshl_b32 s2, s2, 2
	s_bfe_u32 s4, s17, 0x80008
	s_add_u32 s2, s2, s4
	s_lshl_b32 s2, s2, 18
	s_add_u32 s4, s96, s2
	s_addc_u32 s5, s97, 0
	s_lshl_b32 s3, s3, 18
	s_add_u32 s8, s14, s3
	s_addc_u32 s9, s15, 0
	ds_read_b128 v[82:85], v103 offset:32768
	ds_read_b128 v[90:93], v107 offset:32768
	ds_read_b128 v[86:89], v103 offset:36864
	ds_read_b128 v[94:97], v107 offset:36864
	s_waitcnt lgkmcnt(4)
	s_add_u32 m0, s10, 0x0
	v_mfma_f32_32x32x16_bf16 v[2:17], v[74:77], v[66:69], v[2:17]
	global_load_lds_dwordx4 v98, s[4:5]
	s_add_u32 m0, s10, 0x400
	v_mfma_f32_32x32x16_bf16 v[18:33], v[78:81], v[66:69], v[18:33]
	global_load_lds_dwordx4 v99, s[4:5]
	s_add_u32 m0, s10, 0x800
	v_mfma_f32_32x32x16_bf16 v[34:49], v[74:77], v[70:73], v[34:49]
	global_load_lds_dwordx4 v100, s[4:5]
	s_add_u32 m0, s10, 0xc00
	v_mfma_f32_32x32x16_bf16 v[50:65], v[78:81], v[70:73], v[50:65]
	global_load_lds_dwordx4 v101, s[4:5]
	s_add_u32 s4, s4, 128
	s_addc_u32 s5, s5, 0
	ds_read_b128 v[66:69], v104 offset:32768
	ds_read_b128 v[74:77], v108 offset:32768
	ds_read_b128 v[70:73], v104 offset:36864
	ds_read_b128 v[78:81], v108 offset:36864
	s_waitcnt lgkmcnt(4)
	s_add_u32 m0, s10, 0x4000
	v_mfma_f32_32x32x16_bf16 v[2:17], v[90:93], v[82:85], v[2:17]
	global_load_lds_dwordx4 v98, s[8:9]
	s_add_u32 m0, s10, 0x4400
	v_mfma_f32_32x32x16_bf16 v[18:33], v[94:97], v[82:85], v[18:33]
	global_load_lds_dwordx4 v99, s[8:9]
	s_add_u32 m0, s10, 0x4800
	v_mfma_f32_32x32x16_bf16 v[34:49], v[90:93], v[86:89], v[34:49]
	global_load_lds_dwordx4 v100, s[8:9]
	s_add_u32 m0, s10, 0x4c00
	v_mfma_f32_32x32x16_bf16 v[50:65], v[94:97], v[86:89], v[50:65]
	global_load_lds_dwordx4 v101, s[8:9]
	s_add_u32 s8, s8, 128
	s_addc_u32 s9, s9, 0
	ds_read_b128 v[82:85], v105 offset:32768
	ds_read_b128 v[90:93], v109 offset:32768
	ds_read_b128 v[86:89], v105 offset:36864
	ds_read_b128 v[94:97], v109 offset:36864
	s_waitcnt lgkmcnt(4)
	v_mfma_f32_32x32x16_bf16 v[2:17], v[74:77], v[66:69], v[2:17]
	v_mfma_f32_32x32x16_bf16 v[18:33], v[78:81], v[66:69], v[18:33]
	v_mfma_f32_32x32x16_bf16 v[34:49], v[74:77], v[70:73], v[34:49]
	v_mfma_f32_32x32x16_bf16 v[50:65], v[78:81], v[70:73], v[50:65]
	s_waitcnt lgkmcnt(0)
	s_barrier
	v_mfma_f32_32x32x16_bf16 v[2:17], v[90:93], v[82:85], v[2:17]
	v_mfma_f32_32x32x16_bf16 v[18:33], v[94:97], v[82:85], v[18:33]
	v_mfma_f32_32x32x16_bf16 v[34:49], v[90:93], v[86:89], v[34:49]
	v_mfma_f32_32x32x16_bf16 v[50:65], v[94:97], v[86:89], v[50:65]
	s_branch .Lip_kdone

; DI void phase_inproj(const Params& p, int l, char* smem, int tid) {
;     ...
;   for (int it = blockIdx.x; it < 272 * 24; it += gridDim.x) {
.Lip_e1_end:
.Lip_epi_done:
	s_and_b32 s2, s17, 0xff
	s_add_u32 s12, s12, s2
	s_cmpk_lt_u32 s12, 0x330
	s_cbranch_scc1 .Lip_item
